# code placement: the five GEMM K-loop heads aligned to 64 bytes (.p2align 6)
# speedup vs baseline: 1.0047x; 1.0047x over previous
.Lwpf_skip:
	s_ashr_i32 s21, s20, 31
	s_lshl_b64 s[22:23], s[20:21], 19
	s_add_u32 s22, s80, s22
	s_addc_u32 s23, s81, s23
	s_and_b64 s[24:25], s[2:3], exec
	s_cselect_b32 s5, s23, s29
	s_cselect_b32 s21, s22, s28
	s_ashr_i32 s19, s18, 31
	s_lshl_b64 s[24:25], s[18:19], 18
	s_add_u32 s24, s33, s24
	s_addc_u32 s25, s36, s25
	s_and_b64 s[34:35], s[2:3], exec
	s_cselect_b32 s19, s25, s31
	s_cselect_b32 s27, s24, s30
	s_add_u32 s28, s28, 0x40080
	s_addc_u32 s29, s29, 0
	s_add_u32 s60, s30, 0x100
	v_mov_b32_e32 v6, 0
	s_addc_u32 s61, s31, 0
	s_mov_b32 s62, -2
	v_mov_b32_e32 v7, v6
	v_mov_b64_e32 v[8:9], 0
	v_mov_b64_e32 v[10:11], 0
	v_mov_b64_e32 v[12:13], 0
	v_mov_b64_e32 v[22:23], 0
	v_mov_b64_e32 v[24:25], 0
	v_mov_b64_e32 v[26:27], 0
	v_mov_b64_e32 v[28:29], 0
	v_mov_b64_e32 v[38:39], 0
	v_mov_b64_e32 v[40:41], 0
	v_mov_b64_e32 v[42:43], 0
	v_mov_b64_e32 v[44:45], 0
	v_mov_b64_e32 v[54:55], 0
	v_mov_b64_e32 v[56:57], 0
	v_mov_b64_e32 v[58:59], 0
	v_mov_b64_e32 v[60:61], 0
	v_mov_b64_e32 v[14:15], 0
	v_mov_b64_e32 v[16:17], 0
	v_mov_b64_e32 v[18:19], 0
	v_mov_b64_e32 v[20:21], 0
	v_mov_b64_e32 v[30:31], 0
	v_mov_b64_e32 v[32:33], 0
	v_mov_b64_e32 v[34:35], 0
	v_mov_b64_e32 v[36:37], 0
	v_mov_b64_e32 v[46:47], 0
	v_mov_b64_e32 v[48:49], 0
	v_mov_b64_e32 v[50:51], 0
	v_mov_b64_e32 v[52:53], 0
	v_mov_b64_e32 v[62:63], 0
	v_mov_b64_e32 v[64:65], 0
	v_mov_b64_e32 v[66:67], 0
	v_mov_b64_e32 v[68:69], 0
	v_mov_b64_e32 v[70:71], 0
	v_mov_b64_e32 v[72:73], 0
	v_mov_b64_e32 v[74:75], 0
	v_mov_b64_e32 v[76:77], 0
	v_mov_b64_e32 v[86:87], 0
	v_mov_b64_e32 v[88:89], 0
	v_mov_b64_e32 v[90:91], 0
	v_mov_b64_e32 v[92:93], 0
	v_mov_b64_e32 v[102:103], 0
	v_mov_b64_e32 v[104:105], 0
	v_mov_b64_e32 v[106:107], 0
	v_mov_b64_e32 v[108:109], 0
	v_mov_b64_e32 v[118:119], 0
	v_mov_b64_e32 v[120:121], 0
	v_mov_b64_e32 v[122:123], 0
	v_mov_b64_e32 v[124:125], 0
	v_mov_b64_e32 v[78:79], 0
	v_mov_b64_e32 v[80:81], 0
	v_mov_b64_e32 v[82:83], 0
	v_mov_b64_e32 v[84:85], 0
	v_mov_b64_e32 v[94:95], 0
	v_mov_b64_e32 v[96:97], 0
	v_mov_b64_e32 v[98:99], 0
	v_mov_b64_e32 v[100:101], 0
	v_mov_b64_e32 v[110:111], 0
	v_mov_b64_e32 v[112:113], 0
	v_mov_b64_e32 v[114:115], 0
	v_mov_b64_e32 v[116:117], 0
	v_mov_b64_e32 v[126:127], 0
	v_mov_b64_e32 v[128:129], 0
	v_mov_b64_e32 v[130:131], 0
	v_mov_b64_e32 v[132:133], 0
	.p2align	6

.LBB0_204:
	s_ashr_i32 s19, s18, 31
	s_lshl_b64 s[20:21], s[18:19], 19
	s_add_u32 s20, s80, s20
	s_addc_u32 s21, s81, s21
	s_and_b64 s[22:23], s[4:5], exec
	s_cselect_b32 s7, s21, s27
	s_cselect_b32 s19, s20, s26
	s_ashr_i32 s17, s16, 31
	s_lshl_b64 s[22:23], s[16:17], 19
	s_add_u32 s22, s33, s22
	s_addc_u32 s23, s34, s23
	s_and_b64 s[30:31], s[4:5], exec
	s_cselect_b32 s17, s23, s29
	s_cselect_b32 s25, s22, s28
	s_add_u32 s26, s26, 0x40080
	s_addc_u32 s27, s27, 0
	s_add_u32 s48, s28, 0x100
	v_mov_b32_e32 v6, 0
	s_addc_u32 s58, s29, 0
	s_mov_b32 s59, -2
	v_mov_b32_e32 v7, v6
	v_mov_b64_e32 v[8:9], 0
	v_mov_b64_e32 v[10:11], 0
	v_mov_b64_e32 v[12:13], 0
	v_mov_b64_e32 v[22:23], 0
	v_mov_b64_e32 v[24:25], 0
	v_mov_b64_e32 v[26:27], 0
	v_mov_b64_e32 v[28:29], 0
	v_mov_b64_e32 v[38:39], 0
	v_mov_b64_e32 v[40:41], 0
	v_mov_b64_e32 v[42:43], 0
	v_mov_b64_e32 v[44:45], 0
	v_mov_b64_e32 v[70:71], 0
	v_mov_b64_e32 v[72:73], 0
	v_mov_b64_e32 v[74:75], 0
	v_mov_b64_e32 v[76:77], 0
	v_mov_b64_e32 v[14:15], 0
	v_mov_b64_e32 v[16:17], 0
	v_mov_b64_e32 v[18:19], 0
	v_mov_b64_e32 v[20:21], 0
	v_mov_b64_e32 v[30:31], 0
	v_mov_b64_e32 v[32:33], 0
	v_mov_b64_e32 v[34:35], 0
	v_mov_b64_e32 v[36:37], 0
	v_mov_b64_e32 v[62:63], 0
	v_mov_b64_e32 v[64:65], 0
	v_mov_b64_e32 v[66:67], 0
	v_mov_b64_e32 v[68:69], 0
	v_mov_b64_e32 v[78:79], 0
	v_mov_b64_e32 v[80:81], 0
	v_mov_b64_e32 v[82:83], 0
	v_mov_b64_e32 v[84:85], 0
	v_mov_b64_e32 v[86:87], 0
	v_mov_b64_e32 v[88:89], 0
	v_mov_b64_e32 v[90:91], 0
	v_mov_b64_e32 v[92:93], 0
	v_mov_b64_e32 v[102:103], 0
	v_mov_b64_e32 v[104:105], 0
	v_mov_b64_e32 v[106:107], 0
	v_mov_b64_e32 v[108:109], 0
	v_mov_b64_e32 v[118:119], 0
	v_mov_b64_e32 v[120:121], 0
	v_mov_b64_e32 v[122:123], 0
	v_mov_b64_e32 v[124:125], 0
	v_mov_b64_e32 v[134:135], 0
	v_mov_b64_e32 v[136:137], 0
	v_mov_b64_e32 v[138:139], 0
	v_mov_b64_e32 v[140:141], 0
	v_mov_b64_e32 v[94:95], 0
	v_mov_b64_e32 v[96:97], 0
	v_mov_b64_e32 v[98:99], 0
	v_mov_b64_e32 v[100:101], 0
	v_mov_b64_e32 v[110:111], 0
	v_mov_b64_e32 v[112:113], 0
	v_mov_b64_e32 v[114:115], 0
	v_mov_b64_e32 v[116:117], 0
	v_mov_b64_e32 v[126:127], 0
	v_mov_b64_e32 v[128:129], 0
	v_mov_b64_e32 v[130:131], 0
	v_mov_b64_e32 v[132:133], 0
	v_mov_b64_e32 v[142:143], 0
	v_mov_b64_e32 v[144:145], 0
	v_mov_b64_e32 v[146:147], 0
	v_mov_b64_e32 v[148:149], 0
	.p2align	6

.LBB0_299:
	s_cmp_lg_u32 s78, 0
	s_cselect_b64 s[34:35], -1, 0
	s_cmp_eq_u32 s78, 0
	s_cselect_b32 s25, s41, s78
	s_cmp_lt_i32 s25, 1
	s_cbranch_scc1 .LBB0_311
	s_add_i32 s31, s25, -2
	s_add_u32 s36, s36, 0x80
	s_addc_u32 s37, s37, 0
	s_add_u32 s78, s38, 0x100
	v_mov_b32_e32 v6, 0
	s_addc_u32 s79, s39, 0
	s_mov_b32 s38, 0
	v_mov_b32_e32 v7, v6
	v_mov_b64_e32 v[8:9], 0
	v_mov_b64_e32 v[10:11], 0
	v_mov_b64_e32 v[12:13], 0
	v_mov_b64_e32 v[22:23], 0
	v_mov_b64_e32 v[24:25], 0
	v_mov_b64_e32 v[26:27], 0
	v_mov_b64_e32 v[28:29], 0
	v_mov_b64_e32 v[38:39], 0
	v_mov_b64_e32 v[40:41], 0
	v_mov_b64_e32 v[42:43], 0
	v_mov_b64_e32 v[44:45], 0
	v_mov_b64_e32 v[54:55], 0
	v_mov_b64_e32 v[56:57], 0
	v_mov_b64_e32 v[58:59], 0
	v_mov_b64_e32 v[60:61], 0
	v_mov_b64_e32 v[14:15], 0
	v_mov_b64_e32 v[16:17], 0
	v_mov_b64_e32 v[18:19], 0
	v_mov_b64_e32 v[20:21], 0
	v_mov_b64_e32 v[30:31], 0
	v_mov_b64_e32 v[32:33], 0
	v_mov_b64_e32 v[34:35], 0
	v_mov_b64_e32 v[36:37], 0
	v_mov_b64_e32 v[46:47], 0
	v_mov_b64_e32 v[48:49], 0
	v_mov_b64_e32 v[50:51], 0
	v_mov_b64_e32 v[52:53], 0
	v_mov_b64_e32 v[62:63], 0
	v_mov_b64_e32 v[64:65], 0
	v_mov_b64_e32 v[66:67], 0
	v_mov_b64_e32 v[68:69], 0
	v_mov_b64_e32 v[70:71], 0
	v_mov_b64_e32 v[72:73], 0
	v_mov_b64_e32 v[74:75], 0
	v_mov_b64_e32 v[76:77], 0
	v_mov_b64_e32 v[86:87], 0
	v_mov_b64_e32 v[88:89], 0
	v_mov_b64_e32 v[90:91], 0
	v_mov_b64_e32 v[92:93], 0
	v_mov_b64_e32 v[102:103], 0
	v_mov_b64_e32 v[104:105], 0
	v_mov_b64_e32 v[106:107], 0
	v_mov_b64_e32 v[108:109], 0
	v_mov_b64_e32 v[118:119], 0
	v_mov_b64_e32 v[120:121], 0
	v_mov_b64_e32 v[122:123], 0
	v_mov_b64_e32 v[124:125], 0
	v_mov_b64_e32 v[78:79], 0
	v_mov_b64_e32 v[80:81], 0
	v_mov_b64_e32 v[82:83], 0
	v_mov_b64_e32 v[84:85], 0
	v_mov_b64_e32 v[94:95], 0
	v_mov_b64_e32 v[96:97], 0
	v_mov_b64_e32 v[98:99], 0
	v_mov_b64_e32 v[100:101], 0
	v_mov_b64_e32 v[110:111], 0
	v_mov_b64_e32 v[112:113], 0
	v_mov_b64_e32 v[114:115], 0
	v_mov_b64_e32 v[116:117], 0
	v_mov_b64_e32 v[126:127], 0
	v_mov_b64_e32 v[128:129], 0
	v_mov_b64_e32 v[130:131], 0
	v_mov_b64_e32 v[132:133], 0
	.p2align	6

.LBB0_346:
	s_ashr_i32 s27, s26, 31
	s_lshl_b64 s[28:29], s[26:27], 19
	s_add_u32 s28, s80, s28
	s_addc_u32 s29, s81, s29
	s_and_b64 s[30:31], s[4:5], exec
	s_cselect_b32 s3, s29, s9
	s_cselect_b32 s7, s28, s8
	s_ashr_i32 s25, s24, 31
	s_lshl_b64 s[30:31], s[24:25], 19
	s_add_u32 s30, s48, s30
	s_addc_u32 s31, s59, s31
	s_and_b64 s[36:37], s[4:5], exec
	s_cselect_b32 s25, s31, s35
	s_cselect_b32 s27, s30, s34
	s_add_u32 s8, s8, 0x40080
	s_addc_u32 s9, s9, 0
	s_add_u32 s33, s34, 0x100
	v_mov_b32_e32 v8, 0
	s_addc_u32 s38, s35, 0
	s_mov_b32 s39, -2
	v_mov_b32_e32 v9, v8
	v_mov_b32_e32 v10, v8
	v_mov_b32_e32 v11, v8
	v_mov_b32_e32 v12, v8
	v_mov_b32_e32 v13, v8
	v_mov_b32_e32 v14, v8
	v_mov_b32_e32 v15, v8
	v_mov_b32_e32 v24, v8
	v_mov_b32_e32 v25, v8
	v_mov_b32_e32 v26, v8
	v_mov_b32_e32 v27, v8
	v_mov_b32_e32 v28, v8
	v_mov_b32_e32 v29, v8
	v_mov_b32_e32 v30, v8
	v_mov_b32_e32 v31, v8
	v_mov_b32_e32 v56, v8
	v_mov_b32_e32 v57, v8
	v_mov_b32_e32 v58, v8
	v_mov_b32_e32 v59, v8
	v_mov_b32_e32 v60, v8
	v_mov_b32_e32 v61, v8
	v_mov_b32_e32 v62, v8
	v_mov_b32_e32 v63, v8
	v_mov_b32_e32 v96, v8
	v_mov_b32_e32 v97, v8
	v_mov_b32_e32 v98, v8
	v_mov_b32_e32 v99, v8
	v_mov_b32_e32 v100, v8
	v_mov_b32_e32 v101, v8
	v_mov_b32_e32 v102, v8
	v_mov_b32_e32 v103, v8
	v_mov_b32_e32 v16, v8
	v_mov_b32_e32 v17, v8
	v_mov_b32_e32 v18, v8
	v_mov_b32_e32 v19, v8
	v_mov_b32_e32 v20, v8
	v_mov_b32_e32 v21, v8
	v_mov_b32_e32 v22, v8
	v_mov_b32_e32 v23, v8
	v_mov_b32_e32 v32, v8
	v_mov_b32_e32 v33, v8
	v_mov_b32_e32 v34, v8
	v_mov_b32_e32 v35, v8
	v_mov_b32_e32 v36, v8
	v_mov_b32_e32 v37, v8
	v_mov_b32_e32 v38, v8
	v_mov_b32_e32 v39, v8
	v_mov_b32_e32 v72, v8
	v_mov_b32_e32 v73, v8
	v_mov_b32_e32 v74, v8
	v_mov_b32_e32 v75, v8
	v_mov_b32_e32 v76, v8
	v_mov_b32_e32 v77, v8
	v_mov_b32_e32 v78, v8
	v_mov_b32_e32 v79, v8
	v_mov_b32_e32 v104, v8
	v_mov_b32_e32 v105, v8
	v_mov_b32_e32 v106, v8
	v_mov_b32_e32 v107, v8
	v_mov_b32_e32 v108, v8
	v_mov_b32_e32 v109, v8
	v_mov_b32_e32 v110, v8
	v_mov_b32_e32 v111, v8
	v_mov_b32_e32 v112, v8
	v_mov_b32_e32 v113, v8
	v_mov_b32_e32 v114, v8
	v_mov_b32_e32 v115, v8
	v_mov_b32_e32 v116, v8
	v_mov_b32_e32 v117, v8
	v_mov_b32_e32 v118, v8
	v_mov_b32_e32 v119, v8
	v_mov_b32_e32 v128, v8
	v_mov_b32_e32 v129, v8
	v_mov_b32_e32 v130, v8
	v_mov_b32_e32 v131, v8
	v_mov_b32_e32 v132, v8
	v_mov_b32_e32 v133, v8
	v_mov_b32_e32 v134, v8
	v_mov_b32_e32 v135, v8
	v_mov_b32_e32 v144, v8
	v_mov_b32_e32 v145, v8
	v_mov_b32_e32 v146, v8
	v_mov_b32_e32 v147, v8
	v_mov_b32_e32 v148, v8
	v_mov_b32_e32 v149, v8
	v_mov_b32_e32 v150, v8
	v_mov_b32_e32 v151, v8
	v_mov_b32_e32 v160, v8
	v_mov_b32_e32 v161, v8
	v_mov_b32_e32 v162, v8
	v_mov_b32_e32 v163, v8
	v_mov_b32_e32 v164, v8
	v_mov_b32_e32 v165, v8
	v_mov_b32_e32 v166, v8
	v_mov_b32_e32 v167, v8
	v_mov_b32_e32 v120, v8
	v_mov_b32_e32 v121, v8
	v_mov_b32_e32 v122, v8
	v_mov_b32_e32 v123, v8
	v_mov_b32_e32 v124, v8
	v_mov_b32_e32 v125, v8
	v_mov_b32_e32 v126, v8
	v_mov_b32_e32 v127, v8
	v_mov_b32_e32 v136, v8
	v_mov_b32_e32 v137, v8
	v_mov_b32_e32 v138, v8
	v_mov_b32_e32 v139, v8
	v_mov_b32_e32 v140, v8
	v_mov_b32_e32 v141, v8
	v_mov_b32_e32 v142, v8
	v_mov_b32_e32 v143, v8
	v_mov_b32_e32 v152, v8
	v_mov_b32_e32 v153, v8
	v_mov_b32_e32 v154, v8
	v_mov_b32_e32 v155, v8
	v_mov_b32_e32 v156, v8
	v_mov_b32_e32 v157, v8
	v_mov_b32_e32 v158, v8
	v_mov_b32_e32 v159, v8
	v_mov_b32_e32 v168, v8
	v_mov_b32_e32 v169, v8
	v_mov_b32_e32 v170, v8
	v_mov_b32_e32 v171, v8
	v_mov_b32_e32 v172, v8
	v_mov_b32_e32 v173, v8
	v_mov_b32_e32 v174, v8
	v_mov_b32_e32 v175, v8
	.p2align	6

.LBB0_643:
	s_ashr_i32 s11, s10, 31
	s_lshl_b64 s[12:13], s[10:11], 19
	s_add_u32 s12, s26, s12
	s_addc_u32 s13, s27, s13
	s_and_b64 s[14:15], s[2:3], exec
	s_cselect_b32 s11, s13, s21
	s_cselect_b32 s17, s12, s20
	s_ashr_i32 s9, s8, 31
	s_lshl_b64 s[14:15], s[8:9], 19
	s_add_u32 s14, s28, s14
	s_addc_u32 s15, s29, s15
	s_and_b64 s[24:25], s[2:3], exec
	s_cselect_b32 s9, s15, s23
	s_cselect_b32 s41, s14, s22
	s_add_u32 s20, s20, 0x40080
	s_addc_u32 s21, s21, 0
	s_add_u32 s42, s22, 0x100
	v_mov_b32_e32 v6, 0
	s_addc_u32 s43, s23, 0
	s_mov_b32 s44, -2
	v_mov_b32_e32 v7, v6
	v_mov_b64_e32 v[8:9], 0
	v_mov_b64_e32 v[10:11], 0
	v_mov_b64_e32 v[12:13], 0
	v_mov_b64_e32 v[18:19], 0
	v_mov_b64_e32 v[20:21], 0
	v_mov_b64_e32 v[26:27], 0
	v_mov_b64_e32 v[28:29], 0
	v_mov_b64_e32 v[34:35], 0
	v_mov_b64_e32 v[36:37], 0
	v_mov_b64_e32 v[42:43], 0
	v_mov_b64_e32 v[44:45], 0
	v_mov_b64_e32 v[50:51], 0
	v_mov_b64_e32 v[52:53], 0
	v_mov_b64_e32 v[58:59], 0
	v_mov_b64_e32 v[60:61], 0
	v_mov_b64_e32 v[14:15], 0
	v_mov_b64_e32 v[16:17], 0
	v_mov_b64_e32 v[22:23], 0
	v_mov_b64_e32 v[24:25], 0
	v_mov_b64_e32 v[30:31], 0
	v_mov_b64_e32 v[32:33], 0
	v_mov_b64_e32 v[38:39], 0
	v_mov_b64_e32 v[40:41], 0
	v_mov_b64_e32 v[46:47], 0
	v_mov_b64_e32 v[48:49], 0
	v_mov_b64_e32 v[54:55], 0
	v_mov_b64_e32 v[56:57], 0
	v_mov_b64_e32 v[62:63], 0
	v_mov_b64_e32 v[64:65], 0
	v_mov_b64_e32 v[66:67], 0
	v_mov_b64_e32 v[68:69], 0
	v_mov_b64_e32 v[70:71], 0
	v_mov_b64_e32 v[72:73], 0
	v_mov_b64_e32 v[74:75], 0
	v_mov_b64_e32 v[76:77], 0
	v_mov_b64_e32 v[82:83], 0
	v_mov_b64_e32 v[84:85], 0
	v_mov_b64_e32 v[90:91], 0
	v_mov_b64_e32 v[92:93], 0
	v_mov_b64_e32 v[98:99], 0
	v_mov_b64_e32 v[100:101], 0
	v_mov_b64_e32 v[106:107], 0
	v_mov_b64_e32 v[108:109], 0
	v_mov_b64_e32 v[114:115], 0
	v_mov_b64_e32 v[116:117], 0
	v_mov_b64_e32 v[122:123], 0
	v_mov_b64_e32 v[124:125], 0
	v_mov_b64_e32 v[78:79], 0
	v_mov_b64_e32 v[80:81], 0
	v_mov_b64_e32 v[86:87], 0
	v_mov_b64_e32 v[88:89], 0
	v_mov_b64_e32 v[94:95], 0
	v_mov_b64_e32 v[96:97], 0
	v_mov_b64_e32 v[102:103], 0
	v_mov_b64_e32 v[104:105], 0
	v_mov_b64_e32 v[110:111], 0
	v_mov_b64_e32 v[112:113], 0
	v_mov_b64_e32 v[118:119], 0
	v_mov_b64_e32 v[120:121], 0
	v_mov_b64_e32 v[126:127], 0
	v_mov_b64_e32 v[128:129], 0
	v_mov_b64_e32 v[130:131], 0
	v_mov_b64_e32 v[132:133], 0
	.p2align	6
